# mixer-A/C softmax max: two independent v_max3 chains per score half, p0 consumed first so the MFMA-to-VALU wait shrinks from 25 to 12 states; per-instruction s_nop 0 pads removed
# speedup vs baseline: 1.0063x; 1.0063x over previous
; __device__ __forceinline__ float max3f(float a, float b, float c) { float r; asm("v_max3_f32 %0, %1, %2, %3" : "=v"(r) : "v"(a), "v"(b), "v"(c)); return r; }
; __device__ __forceinline__ float max2f(float a, float b) { float r; asm("v_max_f32_e32 %0, %1, %2" : "=v"(r) : "v"(a), "v"(b)); return r; }
; #define ATT_LAS __attribute__((address_space(3)))
; template <int DQK, int MODE> __device__ __forceinline__ void unit(const Desc& d, int q0, ATT_LAS char* shm, const float* biasg, float sinkl2) {
;     ...
;             { const ATT_LAS char* kb = shm + LDS_K + buf * KSLOT + hi * 1024 + r32 * 16;
; #pragma unroll
;               for (int d0 = 0; d0 < ND0; ++d0) {
;                   const bf16x8 b0 = *(const ATT_LAS bf16x8*)(kb + d0 * 2048);
;                   const bf16x8 b1 = *(const ATT_LAS bf16x8*)(kb + d0 * 2048 + 512);
;                   if (d0 == 0) { p0 = __builtin_amdgcn_mfma_f32_32x32x16_bf16(b0, qr[0], negm, 0, 0, 0); p1 = __builtin_amdgcn_mfma_f32_32x32x16_bf16(b1, qr[0], negm, 0, 0, 0); }
;                   else { p0 = __builtin_amdgcn_mfma_f32_32x32x16_bf16(b0, qr[d0], p0, 0, 0, 0); p1 = __builtin_amdgcn_mfma_f32_32x32x16_bf16(b1, qr[d0], p1, 0, 0, 0); } } }
;             if (MODE == 1) {
;                 const ATT_LAS float* bp = bias_l + (64 * t - (qw + r32) + 256 + 4 * hi);
; #pragma unroll
;                 for (int r = 0; r < 16; ++r) { p0[r] += bp[(r & 3) + 8 * (r >> 2)]; p1[r] += bp[(r & 3) + 8 * (r >> 2) + 32]; }
;             }
;             asm volatile("s_nop 15\n\ts_nop 7" : "+v"(p0), "+v"(p1));
;             float rm, rmb;
;             rm = max3f(p0[0], p0[1], p1[0]); rmb = max3f(p0[2], p0[3], p1[1]); rm = max3f(rm, p1[2], p1[3]);
; #pragma unroll
;             for (int r = 4; r < 16; r += 4) { rm = max3f(rm, p0[r], p0[r + 1]); rmb = max3f(rmb, p0[r + 2], p0[r + 3]); rm = max3f(rm, p1[r], p1[r + 1]); rmb = max3f(rmb, p1[r + 2], p1[r + 3]); }
;             rm = max2f(rm, rmb);
;             { auto rr = __builtin_amdgcn_permlane32_swap(__float_as_uint(rm), __float_as_uint(rm), false, false); rm = max2f(__uint_as_float(rr[0]), __uint_as_float(rr[1])); }
.LBB0_548:
	v_add_u32_e32 v0, s41, v124
	v_add_u32_e32 v234, s41, v126
	ds_read_b128 v[134:137], v0
	ds_read_b128 v[138:141], v0 offset:512
	ds_read_b128 v[142:145], v0 offset:2048
	ds_read_b128 v[146:149], v0 offset:2560
	ds_read_b128 v[150:153], v0 offset:4096
	ds_read_b128 v[154:157], v0 offset:4608
	ds_read_b128 v[158:161], v0 offset:6144
	ds_read_b128 v[162:165], v0 offset:6656
	v_mov_b32_e32 v224, s40
	v_mov_b32_e32 v225, s40
	v_mov_b32_e32 v226, s40
	v_mov_b32_e32 v227, s40
	s_waitcnt lgkmcnt(7)
	v_mfma_f32_32x32x16_bf16 v[66:81], v[134:137], v[98:101], v[34:49]
	ds_read_b64_tr_b16 v[166:167], v234
	ds_read_b64_tr_b16 v[168:169], v234 offset:512
	s_waitcnt lgkmcnt(8)
	v_mfma_f32_32x32x16_bf16 v[82:97], v[138:141], v[98:101], v[34:49]
	ds_read_b64_tr_b16 v[170:171], v234 offset:1024
	ds_read_b64_tr_b16 v[172:173], v234 offset:1536
	s_waitcnt lgkmcnt(9)
	v_mfma_f32_32x32x16_bf16 v[66:81], v[142:145], v[102:105], v[66:81]
	ds_read_b64_tr_b16 v[174:175], v234 offset:2048
	ds_read_b64_tr_b16 v[176:177], v234 offset:2560
	s_waitcnt lgkmcnt(10)
	v_mfma_f32_32x32x16_bf16 v[82:97], v[146:149], v[102:105], v[82:97]
	ds_read_b64_tr_b16 v[178:179], v234 offset:3072
	ds_read_b64_tr_b16 v[180:181], v234 offset:3584
	s_waitcnt lgkmcnt(11)
	v_mfma_f32_32x32x16_bf16 v[66:81], v[150:153], v[106:109], v[66:81]
	ds_read_b64_tr_b16 v[182:183], v234 offset:4096
	ds_read_b64_tr_b16 v[184:185], v234 offset:4608
	s_waitcnt lgkmcnt(12)
	v_mfma_f32_32x32x16_bf16 v[82:97], v[154:157], v[106:109], v[82:97]
	ds_read_b64_tr_b16 v[186:187], v234 offset:5120
	ds_read_b64_tr_b16 v[188:189], v234 offset:5632
	s_waitcnt lgkmcnt(13)
	v_mfma_f32_32x32x16_bf16 v[66:81], v[158:161], v[110:113], v[66:81]
	ds_read_b64_tr_b16 v[190:191], v234 offset:6144
	ds_read_b64_tr_b16 v[192:193], v234 offset:6656
	s_waitcnt lgkmcnt(14)
	v_mfma_f32_32x32x16_bf16 v[82:97], v[162:165], v[110:113], v[82:97]
	ds_read_b64_tr_b16 v[194:195], v234 offset:7168
	ds_read_b64_tr_b16 v[196:197], v234 offset:7680
	s_nop 5
	v_max3_f32 v0, v66, v67, v68
	v_max3_f32 v129, v74, v75, v76
	v_max3_f32 v0, v0, v69, v70
	v_max3_f32 v129, v129, v77, v78
	v_max3_f32 v0, v0, v71, v72
	v_max3_f32 v129, v129, v79, v80
	v_max_f32_e32 v0, v0, v73
	v_max_f32_e32 v129, v129, v81
	v_max3_f32 v235, v82, v83, v84
	v_max3_f32 v236, v90, v91, v92
	v_max3_f32 v235, v235, v85, v86
	v_max3_f32 v236, v236, v93, v94
	v_max3_f32 v235, v235, v87, v88
	v_max3_f32 v236, v236, v95, v96
	v_max_f32_e32 v235, v235, v89
	v_max_f32_e32 v236, v236, v97
	v_max3_f32 v0, v0, v129, v235
	v_max_f32_e32 v0, v0, v236
	v_mov_b32_e32 v129, v0
	s_nop 1
	v_permlane32_swap_b32_e32 v0, v129
	v_max_f32_e32 v0, v0, v129
	v_cmp_lt_f32_e32 vcc, s70, v0
	s_cbranch_vccz .LBB0_539
	v_max_f32_e32 v0, v0, v0
	v_max_f32_e32 v0, 0, v0
	s_and_saveexec_b64 s[36:37], s[6:7]
	s_cbranch_execz .LBB0_538
	v_exp_f32_e64 v34, -v0
	ds_write_b32 v125, v34 offset:40960
	s_branch .LBB0_538

; __device__ __forceinline__ float max3f(float a, float b, float c) { float r; asm("v_max3_f32 %0, %1, %2, %3" : "=v"(r) : "v"(a), "v"(b), "v"(c)); return r; }
; __device__ __forceinline__ float max2f(float a, float b) { float r; asm("v_max_f32_e32 %0, %1, %2" : "=v"(r) : "v"(a), "v"(b)); return r; }
; #define ATT_LAS __attribute__((address_space(3)))
; template <int DQK, int MODE> __device__ __forceinline__ void unit(const Desc& d, int q0, ATT_LAS char* shm, const float* biasg, float sinkl2) {
;     ...
;             { const ATT_LAS char* kb = shm + LDS_K + buf * KSLOT + hi * 1024 + r32 * 16;
; #pragma unroll
;               for (int d0 = 0; d0 < ND0; ++d0) {
;                   const bf16x8 b0 = *(const ATT_LAS bf16x8*)(kb + d0 * 2048);
;                   const bf16x8 b1 = *(const ATT_LAS bf16x8*)(kb + d0 * 2048 + 512);
;                   if (d0 == 0) { p0 = __builtin_amdgcn_mfma_f32_32x32x16_bf16(b0, qr[0], negm, 0, 0, 0); p1 = __builtin_amdgcn_mfma_f32_32x32x16_bf16(b1, qr[0], negm, 0, 0, 0); }
;                   else { p0 = __builtin_amdgcn_mfma_f32_32x32x16_bf16(b0, qr[d0], p0, 0, 0, 0); p1 = __builtin_amdgcn_mfma_f32_32x32x16_bf16(b1, qr[d0], p1, 0, 0, 0); } } }
;             if (MODE == 1) {
;                 const ATT_LAS float* bp = bias_l + (64 * t - (qw + r32) + 256 + 4 * hi);
; #pragma unroll
;                 for (int r = 0; r < 16; ++r) { p0[r] += bp[(r & 3) + 8 * (r >> 2)]; p1[r] += bp[(r & 3) + 8 * (r >> 2) + 32]; }
;             }
;             asm volatile("s_nop 15\n\ts_nop 7" : "+v"(p0), "+v"(p1));
;             float rm, rmb;
;             rm = max3f(p0[0], p0[1], p1[0]); rmb = max3f(p0[2], p0[3], p1[1]); rm = max3f(rm, p1[2], p1[3]);
; #pragma unroll
;             for (int r = 4; r < 16; r += 4) { rm = max3f(rm, p0[r], p0[r + 1]); rmb = max3f(rmb, p0[r + 2], p0[r + 3]); rm = max3f(rm, p1[r], p1[r + 1]); rmb = max3f(rmb, p1[r + 2], p1[r + 3]); }
;             rm = max2f(rm, rmb);
;             { auto rr = __builtin_amdgcn_permlane32_swap(__float_as_uint(rm), __float_as_uint(rm), false, false); rm = max2f(__uint_as_float(rr[0]), __uint_as_float(rr[1])); }
.LBB0_586:
	s_mul_i32 s39, s60, 0x3000
	v_add_u32_e32 v0, s39, v209
	v_add_u32_e32 v234, s39, v221
	v_add_u32_e32 v235, s39, v223
	v_add_u32_e32 v236, s39, v252
	v_add_u32_e32 v237, s39, v253
	ds_read_b128 v[130:133], v234
	ds_read_b128 v[134:137], v234 offset:4096
	ds_read_b128 v[138:141], v235
	ds_read_b128 v[142:145], v235 offset:4096
	ds_read_b128 v[146:149], v236
	ds_read_b128 v[150:153], v236 offset:4096
	ds_read_b128 v[154:157], v237
	ds_read_b128 v[158:161], v237 offset:4096
	ds_read_b128 v[162:165], v0 offset:8192
	ds_read_b128 v[166:169], v0 offset:8704
	ds_read_b128 v[170:173], v0 offset:10240
	ds_read_b128 v[174:177], v0 offset:10752
	v_mov_b32_e32 v224, s40
	v_mov_b32_e32 v225, s40
	v_mov_b32_e32 v226, s40
	v_mov_b32_e32 v227, s40
	v_lshl_add_u32 v0, s60, 13, v219
	s_waitcnt lgkmcnt(11)
	v_mfma_f32_32x32x16_bf16 v[114:129], v[130:133], v[178:181], v[66:81]
	ds_read_b64_tr_b16 v[34:35], v0
	s_waitcnt lgkmcnt(11)
	v_mfma_f32_32x32x16_bf16 v[98:113], v[134:137], v[178:181], v[66:81]
	ds_read_b64_tr_b16 v[36:37], v0 offset:512
	s_waitcnt lgkmcnt(11)
	v_mfma_f32_32x32x16_bf16 v[114:129], v[138:141], v[182:185], v[114:129]
	ds_read_b64_tr_b16 v[38:39], v0 offset:1024
	s_waitcnt lgkmcnt(11)
	v_mfma_f32_32x32x16_bf16 v[98:113], v[142:145], v[182:185], v[98:113]
	ds_read_b64_tr_b16 v[40:41], v0 offset:1536
	s_waitcnt lgkmcnt(11)
	v_mfma_f32_32x32x16_bf16 v[114:129], v[146:149], v[186:189], v[114:129]
	ds_read_b64_tr_b16 v[42:43], v0 offset:2048
	s_waitcnt lgkmcnt(11)
	v_mfma_f32_32x32x16_bf16 v[98:113], v[150:153], v[186:189], v[98:113]
	ds_read_b64_tr_b16 v[44:45], v0 offset:2560
	s_waitcnt lgkmcnt(11)
	v_mfma_f32_32x32x16_bf16 v[114:129], v[154:157], v[190:193], v[114:129]
	ds_read_b64_tr_b16 v[46:47], v0 offset:3072
	s_waitcnt lgkmcnt(11)
	v_mfma_f32_32x32x16_bf16 v[98:113], v[158:161], v[190:193], v[98:113]
	ds_read_b64_tr_b16 v[48:49], v0 offset:3584
	s_waitcnt lgkmcnt(11)
	v_mfma_f32_32x32x16_bf16 v[114:129], v[162:165], v[194:197], v[114:129]
	ds_read_b64_tr_b16 v[50:51], v0 offset:4096
	s_waitcnt lgkmcnt(11)
	v_mfma_f32_32x32x16_bf16 v[98:113], v[166:169], v[194:197], v[98:113]
	ds_read_b64_tr_b16 v[52:53], v0 offset:4608
	s_waitcnt lgkmcnt(11)
	v_mfma_f32_32x32x16_bf16 v[114:129], v[170:173], v[198:201], v[114:129]
	ds_read_b64_tr_b16 v[54:55], v0 offset:5120
	s_waitcnt lgkmcnt(11)
	v_mfma_f32_32x32x16_bf16 v[98:113], v[174:177], v[198:201], v[98:113]
	ds_read_b64_tr_b16 v[56:57], v0 offset:5632
	ds_read_b64_tr_b16 v[58:59], v0 offset:6144
	ds_read_b64_tr_b16 v[60:61], v0 offset:6656
	ds_read_b64_tr_b16 v[62:63], v0 offset:7168
	ds_read_b64_tr_b16 v[64:65], v0 offset:7680
	s_nop 4
	v_max3_f32 v0, v114, v115, v116
	v_max3_f32 v222, v122, v123, v124
	v_max3_f32 v0, v0, v117, v118
	v_max3_f32 v222, v222, v125, v126
	v_max3_f32 v0, v0, v119, v120
	v_max3_f32 v222, v222, v127, v128
	v_max_f32_e32 v0, v0, v121
	v_max_f32_e32 v222, v222, v129
	v_max3_f32 v246, v98, v99, v100
	v_max3_f32 v247, v106, v107, v108
	v_max3_f32 v246, v246, v101, v102
	v_max3_f32 v247, v247, v109, v110
	v_max3_f32 v246, v246, v103, v104
	v_max3_f32 v247, v247, v111, v112
	v_max_f32_e32 v246, v246, v105
	v_max_f32_e32 v247, v247, v113
	v_max3_f32 v0, v0, v222, v246
	v_max_f32_e32 v0, v0, v247
	v_mov_b32_e32 v222, v0
	s_nop 1
	v_permlane32_swap_b32_e32 v0, v222
	v_max_f32_e32 v0, v0, v222
	s_cmp_lg_u32 s96, 0
	s_cbranch_scc0 .LBB0_591
	v_cmp_lt_f32_e32 vcc, s70, v0
	s_cbranch_vccz .LBB0_571
	v_max_f32_e32 v250, v0, v0
	v_max_f32_e32 v250, 0, v250
	s_and_saveexec_b64 s[42:43], s[4:5]
	v_exp_f32_e64 v251, -v250
	s_nop 0
	ds_write_b32 v218, v251 offset:40960
	s_or_b64 exec, exec, s[42:43]
	s_waitcnt lgkmcnt(0)
	v_add_u32_e32 v251, s54, v208
	ds_read_b128 v[234:237], v251 offset:40960
	ds_read_b128 v[238:241], v251 offset:40992
	ds_read_b128 v[242:245], v251 offset:41024
	ds_read_b128 v[246:249], v251 offset:41056
	v_add_f32_e32 v220, v220, v250
	v_xor_b32_e32 v81, 0x80000000, v220
	v_sub_f32_e32 v114, v114, v250
	v_sub_f32_e32 v115, v115, v250
	v_sub_f32_e32 v116, v116, v250
	v_sub_f32_e32 v117, v117, v250
	v_sub_f32_e32 v118, v118, v250
	v_sub_f32_e32 v119, v119, v250
	v_sub_f32_e32 v120, v120, v250
	v_sub_f32_e32 v121, v121, v250
	v_sub_f32_e32 v122, v122, v250
	v_sub_f32_e32 v123, v123, v250
	v_sub_f32_e32 v124, v124, v250
	v_sub_f32_e32 v125, v125, v250
	v_sub_f32_e32 v126, v126, v250
	v_sub_f32_e32 v127, v127, v250
	v_sub_f32_e32 v128, v128, v250
	v_sub_f32_e32 v129, v129, v250
	v_sub_f32_e32 v98, v98, v250
	v_sub_f32_e32 v99, v99, v250
	v_sub_f32_e32 v100, v100, v250
	v_sub_f32_e32 v101, v101, v250
	v_sub_f32_e32 v102, v102, v250
	v_sub_f32_e32 v103, v103, v250
	v_sub_f32_e32 v104, v104, v250
	v_sub_f32_e32 v105, v105, v250
	v_sub_f32_e32 v106, v106, v250
	v_sub_f32_e32 v107, v107, v250
	v_sub_f32_e32 v108, v108, v250
	v_sub_f32_e32 v109, v109, v250
	v_sub_f32_e32 v110, v110, v250
	v_sub_f32_e32 v111, v111, v250
	v_sub_f32_e32 v112, v112, v250
	v_sub_f32_e32 v113, v113, v250
	s_waitcnt lgkmcnt(0)
	v_pk_mul_f32 v[2:3], v[2:3], v[234:235]
	v_pk_mul_f32 v[4:5], v[4:5], v[236:237]
	v_pk_mul_f32 v[6:7], v[6:7], v[238:239]
	v_pk_mul_f32 v[8:9], v[8:9], v[240:241]
	v_pk_mul_f32 v[10:11], v[10:11], v[242:243]
	v_pk_mul_f32 v[12:13], v[12:13], v[244:245]
	v_pk_mul_f32 v[14:15], v[14:15], v[246:247]
	v_pk_mul_f32 v[16:17], v[16:17], v[248:249]
	v_pk_mul_f32 v[18:19], v[18:19], v[234:235]
	v_pk_mul_f32 v[20:21], v[20:21], v[236:237]
	v_pk_mul_f32 v[22:23], v[22:23], v[238:239]
	v_pk_mul_f32 v[24:25], v[24:25], v[240:241]
	v_pk_mul_f32 v[26:27], v[26:27], v[242:243]
	v_pk_mul_f32 v[28:29], v[28:29], v[244:245]
	v_pk_mul_f32 v[30:31], v[30:31], v[246:247]
	v_pk_mul_f32 v[32:33], v[32:33], v[248:249]
	v_pk_mul_f32 v[82:83], v[82:83], v[234:235]
	v_pk_mul_f32 v[84:85], v[84:85], v[236:237]
	v_pk_mul_f32 v[86:87], v[86:87], v[238:239]
	v_pk_mul_f32 v[88:89], v[88:89], v[240:241]
	v_pk_mul_f32 v[90:91], v[90:91], v[242:243]
	v_pk_mul_f32 v[92:93], v[92:93], v[244:245]
	v_pk_mul_f32 v[94:95], v[94:95], v[246:247]
	v_pk_mul_f32 v[96:97], v[96:97], v[248:249]
	v_mov_b32_e32 v80, v81
	v_mov_b32_e32 v79, v81
	v_mov_b32_e32 v78, v81
	v_mov_b32_e32 v77, v81
	v_mov_b32_e32 v76, v81
	v_mov_b32_e32 v75, v81
	v_mov_b32_e32 v74, v81
	v_mov_b32_e32 v73, v81
	v_mov_b32_e32 v72, v81
	v_mov_b32_e32 v71, v81
	v_mov_b32_e32 v70, v81
	v_mov_b32_e32 v69, v81
	v_mov_b32_e32 v68, v81
	v_mov_b32_e32 v67, v81
	v_mov_b32_e32 v66, v81
	s_branch .LBB0_571
